# placement flag evaluated right after the first barrier so layer 0 also runs the early differential-attention item
# speedup vs baseline: 1.0117x; 1.0027x over previous
; #define LAS __attribute__((address_space(3)))
; __global__ void __launch_bounds__(256, 2) hybrid_megakernel(Params p, int ph_lo, int ph_hi) {
;     ...
;   XcdBarrier xb = xcd_barrier_post((unsigned*)P_CTR, (volatile LAS unsigned*)&xb_words);
;   for (int ph = ph_lo; ph < ph_hi; ++ph) {
;     if (ph == 1) continue;
;     run_phase(p, ph, smem);
;     if (ph + 1 < ph_hi) {
.LBB0_9:
	s_cmp_lg_u32 s52, 0
	s_cbranch_scc1 .Lev_skip
	s_add_u32 s8, s88, 0x3fc0
	s_addc_u32 s9, s89, 0
	global_load_dwordx4 v[2:5], v1, s[8:9] sc1
	global_load_dwordx4 v[6:9], v1, s[8:9] offset:16 sc1
	v_readlane_b32 s6, v253, 3
	v_readlane_b32 s7, v253, 4
	s_load_dword s6, s[6:7], 0x0
	s_waitcnt vmcnt(0) lgkmcnt(0)
	s_mov_b32 s0, 2
	s_cmpk_lg_u32 s6, 0x200
	s_cbranch_scc1 .Lev_set
	v_readfirstlane_b32 s6, v2
	s_add_i32 s7, s6, -1
	s_and_b32 s7, s7, s6
	s_cbranch_scc1 .Lev_set
	s_cmp_eq_u32 s6, 0
	s_cbranch_scc1 .Lev_set
	v_readfirstlane_b32 s6, v3
	s_add_i32 s7, s6, -1
	s_and_b32 s7, s7, s6
	s_cbranch_scc1 .Lev_set
	s_cmp_eq_u32 s6, 0
	s_cbranch_scc1 .Lev_set
	v_readfirstlane_b32 s6, v4
	s_add_i32 s7, s6, -1
	s_and_b32 s7, s7, s6
	s_cbranch_scc1 .Lev_set
	s_cmp_eq_u32 s6, 0
	s_cbranch_scc1 .Lev_set
	v_readfirstlane_b32 s6, v5
	s_add_i32 s7, s6, -1
	s_and_b32 s7, s7, s6
	s_cbranch_scc1 .Lev_set
	s_cmp_eq_u32 s6, 0
	s_cbranch_scc1 .Lev_set
	v_readfirstlane_b32 s6, v6
	s_add_i32 s7, s6, -1
	s_and_b32 s7, s7, s6
	s_cbranch_scc1 .Lev_set
	s_cmp_eq_u32 s6, 0
	s_cbranch_scc1 .Lev_set
	v_readfirstlane_b32 s6, v7
	s_add_i32 s7, s6, -1
	s_and_b32 s7, s7, s6
	s_cbranch_scc1 .Lev_set
	s_cmp_eq_u32 s6, 0
	s_cbranch_scc1 .Lev_set
	v_readfirstlane_b32 s6, v8
	s_add_i32 s7, s6, -1
	s_and_b32 s7, s7, s6
	s_cbranch_scc1 .Lev_set
	s_cmp_eq_u32 s6, 0
	s_cbranch_scc1 .Lev_set
	v_readfirstlane_b32 s6, v9
	s_add_i32 s7, s6, -1
	s_and_b32 s7, s7, s6
	s_cbranch_scc1 .Lev_set
	s_cmp_eq_u32 s6, 0
	s_cbranch_scc1 .Lev_set
	s_mov_b32 s0, 1
.Lev_set:
	v_writelane_b32 v255, s0, 60
	v_readlane_b32 s6, v253, 0
	s_and_b32 s6, s6, 7
	s_lshl_b32 s6, s6, 7
	s_addk_i32 s6, 0x3800
	s_add_u32 s6, s88, s6
	s_addc_u32 s7, s89, 0
	v_writelane_b32 v255, s6, 58
	v_writelane_b32 v255, s7, 59
.Lev_skip:
	s_cmp_ge_i32 s12, s53
	s_mov_b32 s52, s12
	s_cbranch_scc1 .LBB0_563

; __global__ void __launch_bounds__(256, 2) hybrid_megakernel(Params p, int ph_lo, int ph_hi) {
;     ...
;     if (ph + 1 < ph_hi) {
;       if (ph_hi > 1000) cg::this_grid().sync();
;       xcd_barrier(xb);
;     }
.Llb_have:
	s_cmp_lg_u32 s0, 1
	s_cbranch_scc1 .Llb_global
	s_lshr_b32 s1, 0x21084, s52
	s_bitcmp1_b32 s1, 0
	s_cbranch_scc0 .Lea_no
	v_readlane_b32 s1, v253, 0
	s_cmpk_lt_u32 s1, 0x140
	s_cbranch_scc1 .Lea_no
	v_readlane_b32 s1, v255, 61
	s_cmp_eq_u32 s1, 2
	s_cbranch_scc1 .Lea_no
	s_mov_b32 s1, 1
	v_writelane_b32 v255, s1, 61
	v_writelane_b32 v255, s1, 63
	s_add_i32 s52, s52, 1
	s_branch .LBB0_10
